# phase 0 input staging: a row's four loads issued together (on top of the gla_prep / final_norm / pool_prep / ssd_conv / scale-load de-serialisations)
# speedup vs baseline: 1.0089x; 1.0015x over previous
; DI unsigned pk2(float lo, float hi) { const f32x2v v = {lo, hi}; const bf16x2v b = __builtin_convertvector(v, bf16x2v); return __builtin_bit_cast(unsigned, b); }
; DI void phase0(const Params& P, LAS unsigned char* lds) {
;     ...
;       for (int row = gw; row < T; row += NW) {
;           const float* src = row < TP ? P.in[I_XP] + (size_t)row * DM : P.in[I_XS] + (size_t)(row - TP) * DM;
;           float sq = 0.f;
; #pragma unroll
;           for (int j = 0; j < 4; ++j) { const f32x4 v = *(const f32x4*)(src + lane * 4 + 256 * j);
;               u32x2 w; w.x = pk2(v[0], v[1]); w.y = pk2(v[2], v[3]); *(u32x2*)(XB + (size_t)row * DM + lane * 4 + 256 * j) = w;
;               sq += (v[0] * v[0] + v[1] * v[1]) + (v[2] * v[2] + v[3] * v[3]); }
; #pragma unroll
;           for (int o = 32; o >= 1; o >>= 1) sq += __shfl_xor(sq, o);
;           if (lane < 16) ST[(size_t)row * 16 + lane] = lane == 0 ? sq : 0.f; } }
.LBB0_930:
	s_or_b64 exec, exec, s[10:11]
	s_waitcnt lgkmcnt(0)
	v_lshl_add_u64 v[14:15], v[14:15], 0, v[24:25]
	v_lshlrev_b64 v[26:27], 11, v[12:13]
	v_lshl_add_u64 v[30:31], v[4:5], 0, v[26:27]
	global_load_dwordx4 v[100:103], v[14:15], off
	global_load_dwordx4 v[104:107], v[14:15], off offset:1024
	global_load_dwordx4 v[108:111], v[14:15], off offset:2048
	global_load_dwordx4 v[112:115], v[14:15], off offset:3072
	s_waitcnt vmcnt(0)
	v_mov_b32_e32 v26, v100
	v_mov_b32_e32 v27, v101
	v_mov_b32_e32 v28, v102
	v_mov_b32_e32 v29, v103
	v_mul_f32_e32 v23, v27, v27
	v_cvt_pk_bf16_f32 v32, v26, v27
	v_cvt_pk_bf16_f32 v33, v28, v29
	v_fmac_f32_e32 v23, v26, v26
	v_mul_f32_e32 v26, v29, v29
	global_store_dwordx2 v[30:31], v[32:33], off
	v_fmac_f32_e32 v26, v28, v28
	v_add_f32_e32 v23, v23, v26
	s_nop 0
	v_mov_b32_e32 v26, v104
	v_mov_b32_e32 v27, v105
	v_mov_b32_e32 v28, v106
	v_mov_b32_e32 v29, v107
	v_cvt_pk_bf16_f32 v32, v26, v27
	v_mul_f32_e32 v27, v27, v27
	v_fmac_f32_e32 v27, v26, v26
	v_mul_f32_e32 v26, v29, v29
	v_cvt_pk_bf16_f32 v33, v28, v29
	v_fmac_f32_e32 v26, v28, v28
	global_store_dwordx2 v[30:31], v[32:33], off offset:512
	v_add_f32_e32 v26, v27, v26
	v_add_f32_e32 v23, v23, v26
	s_nop 0
	v_mov_b32_e32 v26, v108
	v_mov_b32_e32 v27, v109
	v_mov_b32_e32 v28, v110
	v_mov_b32_e32 v29, v111
	v_cvt_pk_bf16_f32 v32, v26, v27
	v_mul_f32_e32 v27, v27, v27
	v_fmac_f32_e32 v27, v26, v26
	v_mul_f32_e32 v26, v29, v29
	v_cvt_pk_bf16_f32 v33, v28, v29
	v_fmac_f32_e32 v26, v28, v28
	global_store_dwordx2 v[30:31], v[32:33], off offset:1024
	v_add_f32_e32 v26, v27, v26
	v_add_f32_e32 v23, v23, v26
	s_nop 0
	v_mov_b32_e32 v26, v112
	v_mov_b32_e32 v27, v113
	v_mov_b32_e32 v28, v114
	v_mov_b32_e32 v29, v115
	v_cvt_pk_bf16_f32 v14, v26, v27
	v_cvt_pk_bf16_f32 v15, v28, v29
	global_store_dwordx2 v[30:31], v[14:15], off offset:1536
	v_mul_f32_e32 v14, v27, v27
	v_mul_f32_e32 v15, v29, v29
	v_fmac_f32_e32 v14, v26, v26
	v_fmac_f32_e32 v15, v28, v28
	v_add_f32_e32 v14, v14, v15
	v_add_f32_e32 v14, v23, v14
	ds_bpermute_b32 v15, v1, v14
	s_waitcnt lgkmcnt(0)
	v_add_f32_e32 v14, v14, v15
	ds_bpermute_b32 v15, v3, v14
	s_waitcnt lgkmcnt(0)
	v_add_f32_e32 v14, v14, v15
	ds_bpermute_b32 v15, v19, v14
	s_waitcnt lgkmcnt(0)
	v_add_f32_e32 v14, v14, v15
	ds_bpermute_b32 v15, v20, v14
	s_waitcnt lgkmcnt(0)
	v_add_f32_e32 v14, v14, v15
	ds_bpermute_b32 v15, v21, v14
	s_waitcnt lgkmcnt(0)
	v_add_f32_e32 v14, v14, v15
	ds_bpermute_b32 v15, v22, v14
	s_and_saveexec_b64 s[10:11], vcc
	s_cbranch_execz .LBB0_925
	v_lshlrev_b64 v[12:13], 6, v[12:13]
	s_waitcnt lgkmcnt(0)
	v_add_f32_e32 v14, v14, v15
	v_lshl_add_u64 v[12:13], v[6:7], 0, v[12:13]
	v_cndmask_b32_e64 v14, 0, v14, s[38:39]
	global_store_dword v[12:13], v14, off
	s_branch .LBB0_925
